# speedup vs baseline: 1.0058x; 1.0003x over previous
.LBB0_389:
	s_and_b32 s27, s86, 0xc000
	v_add_u32_e32 v241, s27, v233
	v_xor_b32_e32 v240, 32, v241
	v_xor_b32_e32 v239, 64, v241
	v_xor_b32_e32 v0, 0x60, v241
	s_cmp_gt_u32 s87, 29
	s_cbranch_scc1 .Ltail_c0
	s_add_i32 s3, s86, 0x8000
	s_and_b32 s3, s3, 0xc000
	s_add_u32 s0, s84, s56
	s_addc_u32 s1, s85, s57
	s_add_u32 s10, s0, s40
	s_addc_u32 s11, s1, s41
	s_add_u32 s0, s0, s18
	s_addc_u32 s1, s1, s19
	s_add_i32 m0, s81, s3
	s_nop 0
	global_load_lds_dwordx4 v250, s[0:1]
	s_add_i32 m0, s80, s3
	s_add_i32 s3, s3, 0x2000
	global_load_lds_dwordx4 v251, s[10:11]
	s_add_u32 s0, s0, 0xb8000
	s_addc_u32 s1, s1, 0
	s_add_i32 m0, s81, s3
	s_add_u32 s10, s10, 0xb8000
	s_addc_u32 s11, s11, 0
	global_load_lds_dwordx4 v250, s[0:1]
	s_add_i32 m0, s80, s3
	s_nop 0
	global_load_lds_dwordx4 v251, s[10:11]
	s_waitcnt vmcnt(8)

.LBB0_395:
.Lfz1_c0:
	ds_read_b128 v[144:147], v241 offset:0
	ds_read_b128 v[148:151], v240 offset:0
	ds_read_b128 v[152:155], v239 offset:0
	ds_read_b128 v[156:159], v0 offset:0
	s_waitcnt lgkmcnt(0)
	v_mfma_f32_32x32x16_bf16 v[212:227], v[144:147], v[176:179], 0
	v_mfma_f32_32x32x16_bf16 v[212:227], v[148:151], v[180:183], v[212:227]
	v_mfma_f32_32x32x16_bf16 v[212:227], v[152:155], v[184:187], v[212:227]
	v_mfma_f32_32x32x16_bf16 v[212:227], v[156:159], v[188:191], v[212:227]
	ds_read_b128 v[144:147], v241 offset:0x80
	ds_read_b128 v[148:151], v240 offset:0x80
	ds_read_b128 v[152:155], v239 offset:0x80
	ds_read_b128 v[156:159], v0 offset:0x80
	v_cmp_eq_f32_e32 vcc, 0, v238
	v_cmp_eq_f32_e64 s[10:11], 0, v237
	s_and_b64 s[0:1], vcc, s[10:11]
	s_cmp_eq_u64 s[0:1], exec
	s_waitcnt lgkmcnt(0)
	v_mfma_f32_32x32x16_bf16 v[160:175], v[144:147], v[192:195], 0
	v_mfma_f32_32x32x16_bf16 v[160:175], v[148:151], v[196:199], v[160:175]
	v_mfma_f32_32x32x16_bf16 v[160:175], v[152:155], v[200:203], v[160:175]
	v_mfma_f32_32x32x16_bf16 v[160:175], v[156:159], v[204:207], v[160:175]
	s_cbranch_scc0 .LBB0_397
	v_exp_f32_e32 v144, v212
	v_exp_f32_e32 v145, v213
	v_exp_f32_e32 v146, v214
	v_exp_f32_e32 v147, v215
	v_exp_f32_e32 v148, v216
	v_exp_f32_e32 v149, v217
	v_exp_f32_e32 v150, v218
	v_exp_f32_e32 v151, v219
	v_exp_f32_e32 v152, v220
	v_exp_f32_e32 v153, v221
	v_exp_f32_e32 v154, v222
	v_exp_f32_e32 v155, v223
	v_exp_f32_e32 v156, v224
	v_exp_f32_e32 v157, v225
	v_exp_f32_e32 v158, v226
	v_exp_f32_e32 v159, v227
	v_add_f32_e32 v252, v144, v145
	v_add_f32_e32 v253, v146, v147
	v_add_f32_e32 v254, v148, v149
	v_add_f32_e32 v255, v150, v151
	v_add_f32_e32 v252, v252, v152
	v_add_f32_e32 v253, v253, v153
	v_add_f32_e32 v254, v254, v154
	v_add_f32_e32 v255, v255, v155
	v_add_f32_e32 v252, v252, v156
	v_add_f32_e32 v253, v253, v157
	v_add_f32_e32 v254, v254, v158
	v_add_f32_e32 v255, v255, v159
	v_cvt_pk_bf16_f32 v216, v144, v145
	v_cvt_pk_bf16_f32 v217, v146, v147
	v_add_f32_e32 v252, v252, v253
	v_add_f32_e32 v254, v254, v255
	v_cvt_pk_bf16_f32 v218, v148, v149
	v_cvt_pk_bf16_f32 v219, v150, v151
	v_cvt_pk_bf16_f32 v224, v152, v153
	v_add_f32_e32 v252, v252, v254
	v_cvt_pk_bf16_f32 v225, v154, v155
	v_cvt_pk_bf16_f32 v226, v156, v157
	v_cvt_pk_bf16_f32 v227, v158, v159
	v_add_u32_e32 v253, 0xde801b54, v252
	v_cmp_gt_u32_e32 vcc, 0x3bff7543, v253
	s_cmp_lg_u64 vcc, exec
	s_cbranch_scc1 .LBB0_432
	v_add_f32_e32 v15, v15, v252
	v_exp_f32_e32 v144, v160
	v_exp_f32_e32 v145, v161
	v_exp_f32_e32 v146, v162
	v_exp_f32_e32 v147, v163
	v_exp_f32_e32 v148, v164
	v_exp_f32_e32 v149, v165
	v_exp_f32_e32 v150, v166
	v_exp_f32_e32 v151, v167
	v_exp_f32_e32 v152, v168
	v_exp_f32_e32 v153, v169
	v_exp_f32_e32 v154, v170
	v_exp_f32_e32 v155, v171
	v_exp_f32_e32 v156, v172
	v_exp_f32_e32 v157, v173
	v_exp_f32_e32 v158, v174
	v_exp_f32_e32 v159, v175
	v_add_f32_e32 v252, v144, v145
	v_add_f32_e32 v253, v146, v147
	v_add_f32_e32 v254, v148, v149
	v_add_f32_e32 v255, v150, v151
	v_add_f32_e32 v252, v252, v152
	v_add_f32_e32 v253, v253, v153
	v_add_f32_e32 v254, v254, v154
	v_add_f32_e32 v255, v255, v155
	v_add_f32_e32 v252, v252, v156
	v_add_f32_e32 v253, v253, v157
	v_add_f32_e32 v254, v254, v158
	v_add_f32_e32 v255, v255, v159
	v_cvt_pk_bf16_f32 v212, v144, v145
	v_cvt_pk_bf16_f32 v213, v146, v147
	v_add_f32_e32 v252, v252, v253
	v_add_f32_e32 v254, v254, v255
	v_cvt_pk_bf16_f32 v214, v148, v149
	v_cvt_pk_bf16_f32 v215, v150, v151
	v_cvt_pk_bf16_f32 v220, v152, v153
	v_add_f32_e32 v252, v252, v254
	v_cvt_pk_bf16_f32 v221, v154, v155
	v_cvt_pk_bf16_f32 v222, v156, v157
	v_cvt_pk_bf16_f32 v223, v158, v159
	v_add_u32_e32 v253, 0xde801b54, v252
	v_cmp_gt_u32_e32 vcc, 0x3bff7543, v253
	s_cmp_lg_u64 vcc, exec
	s_cbranch_scc1 .Lfzsb1_c0
	v_add_f32_e32 v14, v14, v252

.LBB0_1243:
	s_and_b32 s27, s77, 0xc000
	v_add_u32_e32 v241, s27, v233
	v_xor_b32_e32 v240, 32, v241
	v_xor_b32_e32 v239, 64, v241
	v_xor_b32_e32 v0, 0x60, v241
	s_cmpk_gt_u32 s79, 0xfd
	s_cbranch_scc1 .Ltail_c1
	s_add_i32 s3, s77, 0x8000
	s_and_b32 s3, s3, 0xc000
	s_add_u32 s0, s69, s86
	s_addc_u32 s1, s76, s87
	s_add_u32 s10, s0, s36
	s_addc_u32 s11, s1, s37
	s_add_u32 s0, s0, s16
	s_addc_u32 s1, s1, s17
	s_add_i32 m0, s68, s3
	s_nop 0
	global_load_lds_dwordx4 v250, s[0:1]
	s_add_i32 m0, s57, s3
	s_add_i32 s3, s3, 0x2000
	global_load_lds_dwordx4 v251, s[10:11]
	s_add_u32 s0, s0, 0xb8000
	s_addc_u32 s1, s1, 0
	s_add_i32 m0, s68, s3
	s_add_u32 s10, s10, 0xb8000
	s_addc_u32 s11, s11, 0
	global_load_lds_dwordx4 v250, s[0:1]
	s_add_i32 m0, s57, s3
	s_nop 0
	global_load_lds_dwordx4 v251, s[10:11]
	s_waitcnt vmcnt(8)

.LBB0_2097:
	s_and_b32 s27, s68, 0xc000
	v_add_u32_e32 v241, s27, v233
	v_xor_b32_e32 v240, 32, v241
	v_xor_b32_e32 v239, 64, v241
	v_xor_b32_e32 v0, 0x60, v241
	s_cmpk_gt_u32 s69, 0xfd
	s_cbranch_scc1 .Ltail_c2
	s_add_i32 s3, s68, 0x8000
	s_and_b32 s3, s3, 0xc000
	s_add_u32 s0, s66, s58
	s_addc_u32 s1, s67, s59
	s_add_u32 s6, s0, s16
	s_addc_u32 s7, s1, s17
	s_add_u32 s0, s0, s14
	s_addc_u32 s1, s1, s15
	s_add_i32 m0, s65, s3
	s_nop 0
	global_load_lds_dwordx4 v250, s[0:1]
	s_add_i32 m0, s64, s3
	s_add_i32 s3, s3, 0x2000
	global_load_lds_dwordx4 v251, s[6:7]
	s_add_u32 s0, s0, 0xb8000
	s_addc_u32 s1, s1, 0
	s_add_i32 m0, s65, s3
	s_add_u32 s6, s6, 0xb8000
	s_addc_u32 s7, s7, 0
	global_load_lds_dwordx4 v250, s[0:1]
	s_add_i32 m0, s64, s3
	s_nop 0
	global_load_lds_dwordx4 v251, s[6:7]
	s_waitcnt vmcnt(8)

.LBB0_2103:
.Lfz1_c2:
	ds_read_b128 v[144:147], v241 offset:0
	ds_read_b128 v[148:151], v240 offset:0
	ds_read_b128 v[152:155], v239 offset:0
	ds_read_b128 v[156:159], v0 offset:0
	s_waitcnt lgkmcnt(0)
	v_mfma_f32_32x32x16_bf16 v[212:227], v[144:147], v[176:179], 0
	v_mfma_f32_32x32x16_bf16 v[212:227], v[148:151], v[180:183], v[212:227]
	v_mfma_f32_32x32x16_bf16 v[212:227], v[152:155], v[184:187], v[212:227]
	v_mfma_f32_32x32x16_bf16 v[212:227], v[156:159], v[188:191], v[212:227]
	ds_read_b128 v[144:147], v241 offset:0x80
	ds_read_b128 v[148:151], v240 offset:0x80
	ds_read_b128 v[152:155], v239 offset:0x80
	ds_read_b128 v[156:159], v0 offset:0x80
	v_cmp_eq_f32_e32 vcc, 0, v238
	v_cmp_eq_f32_e64 s[6:7], 0, v237
	s_and_b64 s[0:1], vcc, s[6:7]
	s_cmp_eq_u64 s[0:1], exec
	s_waitcnt lgkmcnt(0)
	v_mfma_f32_32x32x16_bf16 v[160:175], v[144:147], v[192:195], 0
	v_mfma_f32_32x32x16_bf16 v[160:175], v[148:151], v[196:199], v[160:175]
	v_mfma_f32_32x32x16_bf16 v[160:175], v[152:155], v[200:203], v[160:175]
	v_mfma_f32_32x32x16_bf16 v[160:175], v[156:159], v[204:207], v[160:175]
	s_cbranch_scc0 .LBB0_2105
	v_exp_f32_e32 v144, v212
	v_exp_f32_e32 v145, v213
	v_exp_f32_e32 v146, v214
	v_exp_f32_e32 v147, v215
	v_exp_f32_e32 v148, v216
	v_exp_f32_e32 v149, v217
	v_exp_f32_e32 v150, v218
	v_exp_f32_e32 v151, v219
	v_exp_f32_e32 v152, v220
	v_exp_f32_e32 v153, v221
	v_exp_f32_e32 v154, v222
	v_exp_f32_e32 v155, v223
	v_exp_f32_e32 v156, v224
	v_exp_f32_e32 v157, v225
	v_exp_f32_e32 v158, v226
	v_exp_f32_e32 v159, v227
	v_add_f32_e32 v252, v144, v145
	v_add_f32_e32 v253, v146, v147
	v_add_f32_e32 v254, v148, v149
	v_add_f32_e32 v255, v150, v151
	v_add_f32_e32 v252, v252, v152
	v_add_f32_e32 v253, v253, v153
	v_add_f32_e32 v254, v254, v154
	v_add_f32_e32 v255, v255, v155
	v_add_f32_e32 v252, v252, v156
	v_add_f32_e32 v253, v253, v157
	v_add_f32_e32 v254, v254, v158
	v_add_f32_e32 v255, v255, v159
	v_cvt_pk_bf16_f32 v216, v144, v145
	v_cvt_pk_bf16_f32 v217, v146, v147
	v_add_f32_e32 v252, v252, v253
	v_add_f32_e32 v254, v254, v255
	v_cvt_pk_bf16_f32 v218, v148, v149
	v_cvt_pk_bf16_f32 v219, v150, v151
	v_cvt_pk_bf16_f32 v224, v152, v153
	v_add_f32_e32 v252, v252, v254
	v_cvt_pk_bf16_f32 v225, v154, v155
	v_cvt_pk_bf16_f32 v226, v156, v157
	v_cvt_pk_bf16_f32 v227, v158, v159
	v_add_u32_e32 v253, 0xde801b54, v252
	v_cmp_gt_u32_e32 vcc, 0x3bff7543, v253
	s_cmp_lg_u64 vcc, exec
	s_cbranch_scc1 .LBB0_2140
	v_add_f32_e32 v15, v15, v252
	v_exp_f32_e32 v144, v160
	v_exp_f32_e32 v145, v161
	v_exp_f32_e32 v146, v162
	v_exp_f32_e32 v147, v163
	v_exp_f32_e32 v148, v164
	v_exp_f32_e32 v149, v165
	v_exp_f32_e32 v150, v166
	v_exp_f32_e32 v151, v167
	v_exp_f32_e32 v152, v168
	v_exp_f32_e32 v153, v169
	v_exp_f32_e32 v154, v170
	v_exp_f32_e32 v155, v171
	v_exp_f32_e32 v156, v172
	v_exp_f32_e32 v157, v173
	v_exp_f32_e32 v158, v174
	v_exp_f32_e32 v159, v175
	v_add_f32_e32 v252, v144, v145
	v_add_f32_e32 v253, v146, v147
	v_add_f32_e32 v254, v148, v149
	v_add_f32_e32 v255, v150, v151
	v_add_f32_e32 v252, v252, v152
	v_add_f32_e32 v253, v253, v153
	v_add_f32_e32 v254, v254, v154
	v_add_f32_e32 v255, v255, v155
	v_add_f32_e32 v252, v252, v156
	v_add_f32_e32 v253, v253, v157
	v_add_f32_e32 v254, v254, v158
	v_add_f32_e32 v255, v255, v159
	v_cvt_pk_bf16_f32 v212, v144, v145
	v_cvt_pk_bf16_f32 v213, v146, v147
	v_add_f32_e32 v252, v252, v253
	v_add_f32_e32 v254, v254, v255
	v_cvt_pk_bf16_f32 v214, v148, v149
	v_cvt_pk_bf16_f32 v215, v150, v151
	v_cvt_pk_bf16_f32 v220, v152, v153
	v_add_f32_e32 v252, v252, v254
	v_cvt_pk_bf16_f32 v221, v154, v155
	v_cvt_pk_bf16_f32 v222, v156, v157
	v_cvt_pk_bf16_f32 v223, v158, v159
	v_add_u32_e32 v253, 0xde801b54, v252
	v_cmp_gt_u32_e32 vcc, 0x3bff7543, v253
	s_cmp_lg_u64 vcc, exec
	s_cbranch_scc1 .Lfzsb1_c2
	v_add_f32_e32 v14, v14, v252
